# dead per-tile tid copies removed in the five K/V staging loop heads
# baseline (speedup 1.0000x reference)
; DI void task_nsa(const P& p, int layer, int task, bf16_t* sm, int dm) {
;     ...
;     for (int ct = 0; ct < nct; ++ct, ++itc) {
;       bf16_t* Kl = sm + (itc & 1) * 9216; bf16_t* Vl = Kl + 4608;
;       kv_lstore(R, Kl, Vl);
;       if (ct + 1 < nct) kv_gload(R, kg, 64, vg, 256, (ct + 1) * 64);
.LBB0_666:
	s_bitcmp1_b32 s4, 0
	s_cselect_b32 s7, 0x4800, 0
	s_add_i32 s7, s7, 0
	s_add_i32 s4, s4, 1
	v_add_u32_e32 v32, s7, v235
	s_cmp_ge_u32 s4, s39
	s_waitcnt vmcnt(0)
	ds_write_b128 v32, v[80:83]
	ds_write_b128 v32, v[84:87] offset:9216
	s_cbranch_scc1 .LBB0_668
	v_mov_b32_e32 v36, v195
	s_nop 0
	v_ashrrev_i32_e32 v32, 3, v36
	v_add_u32_e32 v34, s6, v32
	v_ashrrev_i32_e32 v35, 31, v34
	v_lshlrev_b64 v[34:35], 7, v[34:35]
	v_lshlrev_b32_e32 v33, 4, v36
	v_lshl_add_u64 v[34:35], s[28:29], 0, v[34:35]
	v_and_b32_e32 v192, 0x70, v33
	v_lshl_add_u64 v[34:35], v[34:35], 0, v[192:193]
	v_ashrrev_i32_e32 v33, 31, v32
	global_load_dwordx4 v[80:83], v[34:35], off
	v_lshlrev_b64 v[32:33], 9, v[32:33]
	v_and_b32_e32 v34, 7, v36
	v_lshl_or_b32 v32, v34, 4, v32
	v_lshl_add_u64 v[32:33], s[2:3], 0, v[32:33]
	global_load_dwordx4 v[84:87], v[32:33], off

; DI void task_nsa(const P& p, int layer, int task, bf16_t* sm, int dm) {
;     ...
;     for (int ct = 0; ct < nct; ++ct, ++itc) {
;       bf16_t* Kl = sm + (itc & 1) * 9216; bf16_t* Vl = Kl + 4608;
;       kv_lstore(R, Kl, Vl);
;       if (ct + 1 < nct) kv_gload(R, kg, 64, vg, 256, (ct + 1) * 64);
.LBB0_674:
	s_add_i32 s0, s39, s47
	s_bitcmp1_b32 s0, 0
	s_cselect_b32 s0, 0x4800, 0
	s_add_i32 s0, s0, 0
	s_add_i32 s47, s47, 1
	v_add_u32_e32 v0, s0, v235
	s_cmp_ge_u32 s47, s39
	s_waitcnt vmcnt(0)
	ds_write_b128 v0, v[16:19]
	ds_write_b128 v0, v[20:23] offset:9216
	s_cbranch_scc1 .LBB0_676
	v_mov_b32_e32 v4, v195
	s_nop 0
	v_ashrrev_i32_e32 v0, 3, v4
	v_add_u32_e32 v2, s48, v0
	v_ashrrev_i32_e32 v3, 31, v2
	v_lshlrev_b64 v[2:3], 7, v[2:3]
	v_lshlrev_b32_e32 v1, 4, v4
	v_lshl_add_u64 v[2:3], s[28:29], 0, v[2:3]
	v_and_b32_e32 v192, 0x70, v1
	v_lshl_add_u64 v[2:3], v[2:3], 0, v[192:193]
	v_ashrrev_i32_e32 v1, 31, v0
	global_load_dwordx4 v[16:19], v[2:3], off
	v_lshlrev_b64 v[0:1], 9, v[0:1]
	v_and_b32_e32 v2, 7, v4
	v_lshl_or_b32 v0, v2, 4, v0
	v_lshl_add_u64 v[0:1], s[30:31], 0, v[0:1]
	global_load_dwordx4 v[20:23], v[0:1], off

; DI void task_nsa(const P& p, int layer, int task, bf16_t* sm, int dm) {
;     ...
;     for (; todo; ++itc) {
;       const int j = __ffsll((long long)todo) - 1;
;       todo &= todo - 1ull;
;       bf16_t* Kl = sm + (itc & 1) * 9216; bf16_t* Vl = Kl + 4608;
;       kv_lstore(R, Kl, Vl);
;       if (todo) kv_gload(R, kg, 128, vg, S_, (__ffsll((long long)todo) - 1) * 64);
.LBB0_718:
	v_lshl_add_u64 v[2:3], v[0:1], 0, -1
	v_and_b32_e32 v98, v2, v0
	s_bitcmp1_b32 s39, 0
	v_and_b32_e32 v99, v3, v1
	s_cselect_b32 s2, 0x4800, 0
	s_add_i32 s45, s2, 0
	v_cmp_eq_u64_e64 s[2:3], 0, v[98:99]
	v_add_u32_e32 v2, s45, v235
	s_and_b64 vcc, exec, s[2:3]
	s_waitcnt vmcnt(0)
	ds_write_b128 v2, v[80:83]
	ds_write_b128 v2, v[84:87] offset:9216
	s_cbranch_vccnz .LBB0_720
	v_ffbl_b32_e32 v3, v99
	v_ffbl_b32_e32 v2, v98
	v_add_u32_e64 v3, v3, 32 clamp
	v_min_u32_e32 v6, v3, v2
	s_nop 0
	v_readfirstlane_b32 s36, v6
	s_nop 3
	s_lshl_b32 s42, s36, 14
	s_lshl_b32 s36, s36, 7
	s_add_u32 s42, s0, s42
	s_addc_u32 s43, s1, 0
	s_add_u32 s36, s6, s36
	s_addc_u32 s37, s7, 0
	global_load_dwordx4 v[80:83], v223, s[42:43]
	global_load_dwordx4 v[84:87], v224, s[36:37]

; DI void task_nsa(const P& p, int layer, int task, bf16_t* sm, int dm) {
;     ...
;     for (int kt = kt_lo; kt <= kt_hi; ++kt, ++itc) {
;       bf16_t* Kl = sm + (itc & 1) * 9216; bf16_t* Vl = Kl + 4608;
;       kv_lstore(R, Kl, Vl);
;       if (kt < kt_hi) kv_gload(R, kg, 128, vg, S_, (kt + 1) * 64);
.LBB0_808:
	s_bitcmp1_b32 s39, 0
	s_cselect_b32 s0, 0x4800, 0
	s_add_i32 s25, s0, 0
	s_cmp_ge_i32 s45, s35
	s_cselect_b64 s[8:9], -1, 0
	v_add_u32_e32 v0, s25, v235
	s_and_b64 vcc, exec, s[8:9]
	s_waitcnt vmcnt(0)
	ds_write_b128 v0, v[80:83]
	ds_write_b128 v0, v[84:87] offset:9216
	s_cbranch_vccnz .LBB0_810
	s_ashr_i32 s7, s6, 31
	s_add_i32 s36, s6, 64
	s_lshl_b32 s36, s36, 8
	s_add_u32 s36, s2, s36
	s_addc_u32 s37, s3, 0
	s_lshl_b32 s42, s6, 1
	s_add_u32 s42, s4, s42
	s_addc_u32 s43, s5, 0
	global_load_dwordx4 v[80:83], v223, s[36:37]
	global_load_dwordx4 v[84:87], v224, s[42:43] offset:128

; DI void task_attnB(const P& p, int layer, int task, bf16_t* sm, int dm) {
;     ...
;   for (int kt = kt_lo; kt <= kt_hi; ++kt) {
;     bf16_t* Kl = sm + (kt & 1) * 9216; bf16_t* Vl = Kl + 4608;
;     kv_lstore(R, Kl, Vl);
;     if (kt < kt_hi) kv_gload(R, kg, 128, vg, S_, (kt + 1) * 64);
.LBB0_900:
	s_bitcmp1_b32 s30, 0
	s_cselect_b32 s0, 0x4800, 0
	s_add_i32 s31, s0, 0
	s_cmp_ge_i32 s30, s25
	s_cselect_b64 s[8:9], -1, 0
	v_add_u32_e32 v0, s31, v235
	s_and_b64 vcc, exec, s[8:9]
	s_waitcnt vmcnt(0)
	ds_write_b128 v0, v[48:51]
	ds_write_b128 v0, v[52:55] offset:9216
	s_cbranch_vccnz .LBB0_902
	s_ashr_i32 s7, s6, 31
	s_add_i32 s36, s6, 64
	s_lshl_b32 s36, s36, 8
	s_add_u32 s36, s2, s36
	s_addc_u32 s37, s3, 0
	s_lshl_b32 s42, s6, 1
	s_add_u32 s42, s4, s42
	s_addc_u32 s43, s5, 0
	global_load_dwordx4 v[48:51], v223, s[36:37]
	global_load_dwordx4 v[52:55], v224, s[42:43] offset:128
